# batched resid epilogue + index scoring loop pipelined + attention q fragments kept in registers
# speedup vs baseline: 1.0127x; 1.0123x over previous
.LBB0_126:
	s_cmp_gt_i32 s76, -1
	s_cbranch_scc0 .LBB0_138
	s_mul_i32 s0, s22, 0x4200
	s_add_i32 s25, s0, 0
	s_add_u32 s0, s78, 0x2b000000
	s_addc_u32 s1, s79, 0
	s_lshl_b64 s[2:3], s[76:77], 10
	v_and_b32_e32 v1, 63, v2
	s_add_u32 s2, s0, s2
	s_addc_u32 s3, s1, s3
	v_lshlrev_b32_e32 v4, 2, v1
	global_load_dword v124, v4, s[2:3]
	global_load_dword v125, v4, s[2:3] offset:256
	global_load_dword v126, v4, s[2:3] offset:512
	global_load_dword v127, v4, s[2:3] offset:768
	v_mov_b32_e32 v5, v32
	v_lshl_add_u64 v[34:35], s[0:1], 0, v[4:5]
	v_lshlrev_b32_e32 v4, 9, v0
	v_lshl_add_u64 v[6:7], s[16:17], 0, v[4:5]
	v_and_b32_e32 v10, 48, v2
	v_mov_b32_e32 v11, v32
	v_lshlrev_b32_e32 v3, 4, v2
	v_bfe_u32 v1, v2, 4, 2
	v_lshl_add_u64 v[100:101], v[6:7], 0, v[10:11]
	v_and_b32_e32 v6, 0x1f0, v3
	v_mov_b32_e32 v7, v32
	v_lshl_add_u64 v[12:13], s[78:79], 0, v[6:7]
	s_mov_b64 s[0:1], 0x2a300000
	v_lshlrev_b32_e32 v33, 2, v1
	v_lshrrev_b32_e32 v3, 2, v0
	v_lshlrev_b32_e32 v8, 3, v1
	v_lshl_add_u64 v[102:103], v[12:13], 0, s[0:1]
	v_bfe_u32 v7, v2, 5, 1
	v_add_u32_e32 v1, s25, v10
	v_or_b32_e32 v3, v33, v3
	v_mov_b32_e32 v10, s25
	s_movk_i32 s0, 0x210
	v_lshlrev_b32_e32 v2, 3, v2
	v_mov_b32_e32 v9, v32
	v_mad_u32_u24 v10, v3, s0, v10
	v_and_b32_e32 v11, 24, v2
	v_lshl_add_u64 v[2:3], s[78:79], 0, v[4:5]
	v_lshl_add_u64 v[2:3], v[2:3], 0, v[8:9]
	s_mov_b64 s[0:1], 0x2c000000
	v_lshl_add_u64 v[104:105], v[2:3], 0, s[0:1]
	v_cmp_lt_i32_e32 vcc, v186, v181
	s_lshl_b32 s0, s10, 11
	s_and_b32 s0, s0, 0x3000
	v_cndmask_b32_e32 v4, v179, v186, vcc
	v_cmp_lt_i32_e32 vcc, v187, v181
	v_add_u32_e32 v6, s25, v6
	v_mul_u32_u24_e32 v2, 0x210, v7
	v_mul_u32_u24_e32 v3, 0x210, v0
	v_lshlrev_b32_e32 v113, 2, v4
	v_cndmask_b32_e32 v4, v179, v187, vcc
	s_add_i32 s24, s24, s0
	v_readlane_b32 s0, v252, 29
	s_mov_b32 s2, 0
	v_or_b32_e32 v110, 1, v180
	v_or_b32_e32 v111, 2, v180
	v_or_b32_e32 v112, 3, v180
	v_lshlrev_b32_e32 v114, 2, v4
	v_or_b32_e32 v115, v180, v7
	v_lshl_add_u32 v116, v0, 2, s0
	v_add_u32_e32 v117, v6, v2
	v_add_u32_e32 v118, v1, v3
	v_add_u32_e32 v119, v10, v11
	s_waitcnt vmcnt(0)

.LBB0_135:
	s_and_b32 s0, s76, 0x7ffff000
	s_mov_b32 s1, s77
	s_lshl_b64 s[0:1], s[0:1], 9
	v_mov_b32_e32 v72, 0
	s_and_b32 s29, s76, 0xfff
	v_mad_u64_u32 v[106:107], s[2:3], s76, v188, v[100:101]
	v_lshl_add_u64 v[108:109], v[102:103], 0, s[0:1]
	v_mov_b32_e32 v128, 0xff800000
	global_load_dwordx4 v[196:199], v[106:107], off
	global_load_dwordx4 v[200:203], v[106:107], off offset:64
	global_load_dwordx4 v[204:207], v[106:107], off offset:128
	global_load_dwordx4 v[208:211], v[106:107], off offset:192
	global_load_dwordx4 v[212:215], v[106:107], off offset:256
	global_load_dwordx4 v[216:219], v[106:107], off offset:320
	global_load_dwordx4 v[220:223], v[106:107], off offset:384
	global_load_dwordx4 v[224:227], v[106:107], off offset:448
	s_mov_b32 s30, 0
	v_mov_b32_e32 v68, 0
	v_mov_b32_e32 v69, v72
	v_mov_b32_e32 v70, v72
	v_mov_b32_e32 v71, v72
	v_mov_b32_e32 v24, 0
	v_mov_b32_e32 v25, v72
	v_mov_b32_e32 v26, v72
	v_mov_b32_e32 v27, v72
	v_mov_b32_e32 v64, 0
	v_mov_b32_e32 v65, v72
	v_mov_b32_e32 v66, v72
	v_mov_b32_e32 v67, v72
	v_mov_b32_e32 v60, 0
	v_mov_b32_e32 v61, v72
	v_mov_b32_e32 v62, v72
	v_mov_b32_e32 v63, v72
	v_mov_b32_e32 v56, 0
	v_mov_b32_e32 v57, v72
	v_mov_b32_e32 v58, v72
	v_mov_b32_e32 v59, v72
	v_mov_b32_e32 v52, 0
	v_mov_b32_e32 v53, v72
	v_mov_b32_e32 v54, v72
	v_mov_b32_e32 v55, v72
	v_mov_b32_e32 v48, 0
	v_mov_b32_e32 v49, v72
	v_mov_b32_e32 v50, v72
	v_mov_b32_e32 v51, v72
	v_mov_b32_e32 v44, 0
	v_mov_b32_e32 v45, v72
	v_mov_b32_e32 v46, v72
	v_mov_b32_e32 v47, v72
	v_mov_b32_e32 v40, 0
	v_mov_b32_e32 v41, v72
	v_mov_b32_e32 v42, v72
	v_mov_b32_e32 v43, v72
	v_mov_b32_e32 v28, 0
	v_mov_b32_e32 v29, v72
	v_mov_b32_e32 v30, v72
	v_mov_b32_e32 v31, v72
	v_mov_b32_e32 v20, 0
	v_mov_b32_e32 v21, v72
	v_mov_b32_e32 v22, v72
	v_mov_b32_e32 v23, v72
	v_mov_b32_e32 v16, 0
	v_mov_b32_e32 v17, v72
	v_mov_b32_e32 v18, v72
	v_mov_b32_e32 v19, v72
	v_mov_b32_e32 v12, 0
	v_mov_b32_e32 v13, v72
	v_mov_b32_e32 v14, v72
	v_mov_b32_e32 v15, v72
	v_mov_b32_e32 v8, 0
	v_mov_b32_e32 v9, v72
	v_mov_b32_e32 v10, v72
	v_mov_b32_e32 v11, v72
	v_mov_b32_e32 v4, 0
	v_mov_b32_e32 v5, v72
	v_mov_b32_e32 v6, v72
	v_mov_b32_e32 v7, v72
	v_mov_b32_e32 v0, 0
	v_mov_b32_e32 v1, v72
	v_mov_b32_e32 v2, v72
	v_mov_b32_e32 v3, v72
.LBB0_136:
	s_lshr_b32 s2, s30, 1
	s_cmp_lt_u32 s30, 2
	s_cselect_b64 vcc, -1, 0
	s_cmp_eq_u32 s2, 1
	s_cselect_b64 s[0:1], -1, 0
	s_cmp_eq_u32 s2, 2
	s_cselect_b64 s[2:3], -1, 0
	v_mov_b32_e32 v129, v72
	v_cndmask_b32_e64 v72, v127, v126, s[2:3]
	v_cndmask_b32_e64 v72, v72, v125, s[0:1]
	s_and_b32 s0, s28, 32
	v_cndmask_b32_e32 v130, v72, v124, vcc
	v_or_b32_e32 v72, s0, v115
	v_lshlrev_b32_e32 v131, 2, v72
	ds_bpermute_b32 v72, v131, v130
	ds_bpermute_b32 v76, v131, v130 offset:8
	ds_bpermute_b32 v80, v131, v130 offset:16
	ds_bpermute_b32 v84, v131, v130 offset:24
	ds_bpermute_b32 v88, v131, v130 offset:32
	ds_bpermute_b32 v92, v131, v130 offset:40
	ds_bpermute_b32 v96, v131, v130 offset:48
	ds_bpermute_b32 v132, v131, v130 offset:56
	ds_bpermute_b32 v136, v131, v130 offset:64
	ds_bpermute_b32 v140, v131, v130 offset:72
	s_waitcnt lgkmcnt(9)
	v_max_i32_e32 v72, 0, v72
	s_waitcnt lgkmcnt(8)
	v_max_i32_e32 v76, 0, v76
	s_waitcnt lgkmcnt(7)
	v_max_i32_e32 v80, 0, v80
	s_waitcnt lgkmcnt(6)
	v_max_i32_e32 v84, 0, v84
	v_lshlrev_b32_e32 v72, 8, v72
	v_mov_b32_e32 v73, v32
	v_lshlrev_b32_e32 v76, 8, v76
	v_mov_b32_e32 v77, v32
	v_lshlrev_b32_e32 v80, 8, v80
	v_mov_b32_e32 v81, v32
	v_lshlrev_b32_e32 v84, 8, v84
	v_mov_b32_e32 v85, v32
	s_waitcnt lgkmcnt(5)
	v_max_i32_e32 v88, 0, v88
	s_waitcnt lgkmcnt(4)
	v_max_i32_e32 v92, 0, v92
	s_waitcnt lgkmcnt(3)
	v_max_i32_e32 v96, 0, v96
	s_waitcnt lgkmcnt(2)
	v_max_i32_e32 v132, 0, v132
	v_lshl_add_u64 v[72:73], v[72:73], 1, v[108:109]
	v_lshl_add_u64 v[76:77], v[76:77], 1, v[108:109]
	v_lshl_add_u64 v[80:81], v[80:81], 1, v[108:109]
	v_lshl_add_u64 v[84:85], v[84:85], 1, v[108:109]
	v_lshlrev_b32_e32 v88, 8, v88
	v_mov_b32_e32 v89, v32
	v_lshlrev_b32_e32 v92, 8, v92
	v_mov_b32_e32 v93, v32
	v_lshlrev_b32_e32 v96, 8, v96
	v_mov_b32_e32 v97, v32
	v_lshlrev_b32_e32 v132, 8, v132
	v_mov_b32_e32 v133, v32
	s_waitcnt lgkmcnt(1)
	v_max_i32_e32 v136, 0, v136
	s_waitcnt lgkmcnt(0)
	v_max_i32_e32 v140, 0, v140
	global_load_dwordx4 v[72:75], v[72:73], off
	v_lshl_add_u64 v[88:89], v[88:89], 1, v[108:109]
	global_load_dwordx4 v[76:79], v[76:77], off
	v_lshl_add_u64 v[92:93], v[92:93], 1, v[108:109]
	global_load_dwordx4 v[80:83], v[80:81], off
	v_lshl_add_u64 v[96:97], v[96:97], 1, v[108:109]
	global_load_dwordx4 v[84:87], v[84:85], off
	v_lshl_add_u64 v[132:133], v[132:133], 1, v[108:109]
	v_lshlrev_b32_e32 v136, 8, v136
	v_mov_b32_e32 v137, v32
	v_lshlrev_b32_e32 v140, 8, v140
	v_mov_b32_e32 v141, v32
	global_load_dwordx4 v[88:91], v[88:89], off
	v_lshl_add_u64 v[136:137], v[136:137], 1, v[108:109]
	global_load_dwordx4 v[92:95], v[92:93], off
	v_lshl_add_u64 v[140:141], v[140:141], 1, v[108:109]
	global_load_dwordx4 v[96:99], v[96:97], off
	s_add_i32 s30, s30, 1
	global_load_dwordx4 v[132:135], v[132:133], off
	global_load_dwordx4 v[136:139], v[136:137], off
	s_add_i32 s28, s28, 32
	global_load_dwordx4 v[144:147], v[140:141], off
	ds_bpermute_b32 v140, v131, v130 offset:80
	v_mov_b32_e32 v141, v32
	s_cmp_eq_u32 s30, 8
	s_waitcnt lgkmcnt(0)
	v_max_i32_e32 v140, 0, v140
	v_lshlrev_b32_e32 v140, 8, v140
	v_lshl_add_u64 v[140:141], v[140:141], 1, v[108:109]
	global_load_dwordx4 v[148:151], v[140:141], off
	ds_bpermute_b32 v140, v131, v130 offset:88
	v_mov_b32_e32 v141, v32
	s_waitcnt lgkmcnt(0)
	v_max_i32_e32 v140, 0, v140
	v_lshlrev_b32_e32 v140, 8, v140
	v_lshl_add_u64 v[140:141], v[140:141], 1, v[108:109]
	global_load_dwordx4 v[152:155], v[140:141], off
	ds_bpermute_b32 v140, v131, v130 offset:96
	v_mov_b32_e32 v141, v32
	s_waitcnt lgkmcnt(0)
	v_max_i32_e32 v140, 0, v140
	v_lshlrev_b32_e32 v140, 8, v140
	v_lshl_add_u64 v[140:141], v[140:141], 1, v[108:109]
	global_load_dwordx4 v[156:159], v[140:141], off
	ds_bpermute_b32 v140, v131, v130 offset:104
	v_mov_b32_e32 v141, v32
	s_waitcnt lgkmcnt(0)
	v_max_i32_e32 v140, 0, v140
	v_lshlrev_b32_e32 v140, 8, v140
	v_lshl_add_u64 v[140:141], v[140:141], 1, v[108:109]
	global_load_dwordx4 v[160:163], v[140:141], off
	ds_bpermute_b32 v140, v131, v130 offset:112
	ds_bpermute_b32 v131, v131, v130 offset:120
	v_mov_b32_e32 v141, v32
	s_waitcnt lgkmcnt(1)
	v_max_i32_e32 v140, 0, v140
	v_lshlrev_b32_e32 v140, 8, v140
	v_lshl_add_u64 v[140:141], v[140:141], 1, v[108:109]
	s_waitcnt lgkmcnt(0)
	v_max_i32_e32 v131, 0, v131
	global_load_dwordx4 v[172:175], v[140:141], off
	v_lshlrev_b32_e32 v140, 8, v131
	v_mov_b32_e32 v141, v32
	v_lshl_add_u64 v[140:141], v[140:141], 1, v[108:109]
	global_load_dwordx4 v[192:195], v[140:141], off
	s_waitcnt vmcnt(15)
	ds_write_b128 v117, v[72:75]
	s_waitcnt vmcnt(14)
	ds_write_b128 v117, v[76:79] offset:1056
	s_waitcnt vmcnt(13)
	ds_write_b128 v117, v[80:83] offset:2112
	s_waitcnt vmcnt(12)
	ds_write_b128 v117, v[84:87] offset:3168
	s_waitcnt vmcnt(11)
	ds_write_b128 v117, v[88:91] offset:4224
	s_waitcnt vmcnt(10)
	ds_write_b128 v117, v[92:95] offset:5280
	s_waitcnt vmcnt(9)
	ds_write_b128 v117, v[96:99] offset:6336
	s_waitcnt vmcnt(8)
	ds_write_b128 v117, v[132:135] offset:7392
	s_waitcnt vmcnt(7)
	ds_write_b128 v117, v[136:139] offset:8448
	s_waitcnt vmcnt(6)
	ds_write_b128 v117, v[144:147] offset:9504
	s_waitcnt vmcnt(5)
	ds_write_b128 v117, v[148:151] offset:10560
	s_waitcnt vmcnt(4)
	ds_write_b128 v117, v[152:155] offset:11616
	s_waitcnt vmcnt(3)
	ds_write_b128 v117, v[156:159] offset:12672
	s_waitcnt vmcnt(2)
	ds_write_b128 v117, v[160:163] offset:13728
	s_waitcnt vmcnt(1)
	ds_write_b128 v117, v[172:175] offset:14784
	s_waitcnt vmcnt(0)
	ds_write_b128 v117, v[192:195] offset:15840
	v_or_b32_e32 v72, s0, v33
	v_or_b32_e32 v73, v72, v180
	v_lshlrev_b32_e32 v73, 2, v73
	ds_bpermute_b32 v138, v73, v130
	v_or_b32_e32 v73, v72, v110
	v_lshlrev_b32_e32 v73, 2, v73
	ds_bpermute_b32 v139, v73, v130
	v_or_b32_e32 v73, v72, v111
	v_lshlrev_b32_e32 v73, 2, v73
	ds_bpermute_b32 v140, v73, v130
	v_or_b32_e32 v73, v72, v112
	v_lshlrev_b32_e32 v73, 2, v73
	v_or_b32_e32 v72, 16, v72
	ds_bpermute_b32 v141, v73, v130
	v_or_b32_e32 v73, v72, v180
	v_lshlrev_b32_e32 v73, 2, v73
	ds_bpermute_b32 v142, v73, v130
	v_or_b32_e32 v73, v72, v110
	v_lshlrev_b32_e32 v73, 2, v73
	ds_bpermute_b32 v143, v73, v130
	v_or_b32_e32 v73, v72, v111
	v_or_b32_e32 v72, v72, v112
	v_lshlrev_b32_e32 v73, 2, v73
	v_lshlrev_b32_e32 v72, 2, v72
	s_mov_b64 s[0:1], 0
	ds_bpermute_b32 v148, v73, v130
	ds_bpermute_b32 v149, v72, v130
	s_waitcnt lgkmcnt(7)
	v_cmp_lt_i32_e32 vcc, -1, v138
	s_waitcnt lgkmcnt(0)
	ds_read_b128 v[228:231], v118
	ds_read_b128 v[232:235], v118 offset:64
	ds_read_b128 v[236:239], v118 offset:128
	ds_read_b128 v[240:243], v118 offset:192
	s_waitcnt lgkmcnt(3)
	v_mfma_f32_16x16x32_bf16 v[134:137], v[228:231], v[196:199], 0
	ds_read_b128 v[228:231], v118 offset:256
	s_waitcnt lgkmcnt(3)
	v_mfma_f32_16x16x32_bf16 v[134:137], v[232:235], v[200:203], v[134:137]
	ds_read_b128 v[232:235], v118 offset:320
	s_waitcnt lgkmcnt(3)
	v_mfma_f32_16x16x32_bf16 v[134:137], v[236:239], v[204:207], v[134:137]
	ds_read_b128 v[236:239], v118 offset:384
	s_waitcnt lgkmcnt(3)
	v_mfma_f32_16x16x32_bf16 v[134:137], v[240:243], v[208:211], v[134:137]
	ds_read_b128 v[240:243], v118 offset:448
	s_waitcnt lgkmcnt(3)
	v_mfma_f32_16x16x32_bf16 v[134:137], v[228:231], v[212:215], v[134:137]
	ds_read_b128 v[228:231], v118 offset:8448
	s_waitcnt lgkmcnt(3)
	v_mfma_f32_16x16x32_bf16 v[134:137], v[232:235], v[216:219], v[134:137]
	ds_read_b128 v[232:235], v118 offset:8512
	s_waitcnt lgkmcnt(3)
	v_mfma_f32_16x16x32_bf16 v[134:137], v[236:239], v[220:223], v[134:137]
	ds_read_b128 v[236:239], v118 offset:8576
	s_waitcnt lgkmcnt(3)
	v_mfma_f32_16x16x32_bf16 v[134:137], v[240:243], v[224:227], v[134:137]
	ds_read_b128 v[240:243], v118 offset:8640
	s_waitcnt lgkmcnt(3)
	v_mfma_f32_16x16x32_bf16 v[72:75], v[228:231], v[196:199], 0
	ds_read_b128 v[228:231], v118 offset:8704
	s_waitcnt lgkmcnt(3)
	v_mfma_f32_16x16x32_bf16 v[72:75], v[232:235], v[200:203], v[72:75]
	ds_read_b128 v[232:235], v118 offset:8768
	s_waitcnt lgkmcnt(3)
	v_mfma_f32_16x16x32_bf16 v[72:75], v[236:239], v[204:207], v[72:75]
	ds_read_b128 v[236:239], v118 offset:8832
	s_waitcnt lgkmcnt(3)
	v_mfma_f32_16x16x32_bf16 v[72:75], v[240:243], v[208:211], v[72:75]
	ds_read_b128 v[240:243], v118 offset:8896
	v_subrev_u32_e32 v80, s29, v142
	v_med3_i32 v80, v80, s4, v189
	v_lshl_add_u32 v80, v80, 6, v116
	ds_read_b32 v80, v80 offset:8192
	s_waitcnt lgkmcnt(4)
	v_mfma_f32_16x16x32_bf16 v[72:75], v[228:231], v[212:215], v[72:75]
	s_waitcnt lgkmcnt(3)
	v_mfma_f32_16x16x32_bf16 v[72:75], v[232:235], v[216:219], v[72:75]
	s_waitcnt lgkmcnt(2)
	v_mfma_f32_16x16x32_bf16 v[72:75], v[236:239], v[220:223], v[72:75]
	s_waitcnt lgkmcnt(1)
	v_mfma_f32_16x16x32_bf16 v[72:75], v[240:243], v[224:227], v[72:75]
	v_subrev_u32_e32 v76, s29, v138
	v_med3_i32 v76, v76, s4, v189
	v_subrev_u32_e32 v77, s29, v139
	v_lshl_add_u32 v76, v76, 6, v116
	v_med3_i32 v77, v77, s4, v189
	v_subrev_u32_e32 v78, s29, v140
	ds_read_b32 v76, v76 offset:8192
	v_lshl_add_u32 v77, v77, 6, v116
	v_med3_i32 v78, v78, s4, v189
	v_subrev_u32_e32 v79, s29, v141
	ds_read_b32 v77, v77 offset:8192
	v_lshl_add_u32 v78, v78, 6, v116
	v_med3_i32 v79, v79, s4, v189
	ds_read_b32 v78, v78 offset:8192
	v_lshl_add_u32 v79, v79, 6, v116
	ds_read_b32 v79, v79 offset:8192
	s_waitcnt lgkmcnt(3)
	v_fmac_f32_e32 v76, 0x3d800000, v134
	v_cndmask_b32_e32 v76, v190, v76, vcc
	s_waitcnt lgkmcnt(2)
	v_fmac_f32_e32 v77, 0x3d800000, v135
	v_cmp_lt_i32_e32 vcc, -1, v139
	s_waitcnt lgkmcnt(1)
	v_fmac_f32_e32 v78, 0x3d800000, v136
	s_waitcnt lgkmcnt(0)
	v_fmac_f32_e32 v79, 0x3d800000, v137
	v_cndmask_b32_e32 v77, v190, v77, vcc
	v_cmp_lt_i32_e32 vcc, -1, v140
	v_fmac_f32_e32 v80, 0x3d800000, v72
	s_nop 0
	v_cndmask_b32_e32 v78, v190, v78, vcc
	v_cmp_lt_i32_e32 vcc, -1, v141
	s_nop 1
	v_cndmask_b32_e32 v79, v190, v79, vcc
	v_cmp_lt_i32_e32 vcc, -1, v142
	v_max_f32_e32 v81, v78, v79
	s_nop 0
	v_cndmask_b32_e32 v72, v190, v80, vcc
	v_subrev_u32_e32 v80, s29, v143
	v_med3_i32 v80, v80, s4, v189
	v_lshl_add_u32 v80, v80, 6, v116
	ds_read_b32 v80, v80 offset:8192
	v_cmp_lt_i32_e32 vcc, -1, v143
	s_waitcnt lgkmcnt(0)
	v_fmac_f32_e32 v80, 0x3d800000, v73
	v_subrev_u32_e32 v73, s29, v148
	v_med3_i32 v73, v73, s4, v189
	v_lshl_add_u32 v73, v73, 6, v116
	ds_read_b32 v73, v73 offset:8192
	v_cndmask_b32_e32 v80, v190, v80, vcc
	v_cmp_lt_i32_e32 vcc, -1, v148
	s_waitcnt lgkmcnt(0)
	v_fmac_f32_e32 v73, 0x3d800000, v74
	v_cndmask_b32_e32 v74, v190, v73, vcc
	v_subrev_u32_e32 v73, s29, v149
	v_med3_i32 v73, v73, s4, v189
	v_lshl_add_u32 v73, v73, 6, v116
	ds_read_b32 v73, v73 offset:8192
	v_cmp_lt_i32_e32 vcc, -1, v149
	s_waitcnt lgkmcnt(0)
	v_fmac_f32_e32 v73, 0x3d800000, v75
	v_cndmask_b32_e32 v75, v190, v73, vcc
	v_max_f32_e32 v82, v74, v75
	v_max_f32_e32 v73, v76, v77
	v_max3_f32 v82, v72, v80, v82
	v_max3_f32 v73, v73, v81, v82
	ds_bpermute_b32 v81, v113, v73
	s_waitcnt lgkmcnt(0)
	v_max_f32_e32 v81, v81, v81
	v_max_f32_e32 v73, v73, v81
	ds_bpermute_b32 v81, v114, v73
	s_waitcnt lgkmcnt(0)
	v_max3_f32 v73, v128, v73, v81
	v_sub_f32_e32 v72, v72, v73
	v_mul_f32_e32 v72, 0x3fb8aa3b, v72
	v_sub_f32_e32 v76, v76, v73
	v_exp_f32_e32 v82, v72
	v_sub_f32_e32 v72, v80, v73
	v_mul_f32_e32 v76, 0x3fb8aa3b, v76
	v_sub_f32_e32 v77, v77, v73
	v_mul_f32_e32 v72, 0x3fb8aa3b, v72
	v_exp_f32_e32 v76, v76
	v_mul_f32_e32 v77, 0x3fb8aa3b, v77
	v_sub_f32_e32 v78, v78, v73
	v_exp_f32_e32 v80, v72
	v_sub_f32_e32 v72, v74, v73
	v_exp_f32_e32 v77, v77
	v_mul_f32_e32 v78, 0x3fb8aa3b, v78
	v_sub_f32_e32 v79, v79, v73
	v_mul_f32_e32 v72, 0x3fb8aa3b, v72
	v_exp_f32_e32 v78, v78
	v_mul_f32_e32 v79, 0x3fb8aa3b, v79
	v_exp_f32_e32 v83, v72
	v_sub_f32_e32 v72, v75, v73
	v_exp_f32_e32 v79, v79
	v_mul_f32_e32 v72, 0x3fb8aa3b, v72
	v_exp_f32_e32 v84, v72
	v_add_f32_e32 v72, 0, v76
	v_add_f32_e32 v72, v77, v72
	v_add_f32_e32 v72, v78, v72
	v_sub_f32_e32 v81, v128, v73
	v_add_f32_e32 v72, v79, v72
	v_mul_f32_e32 v81, 0x3fb8aa3b, v81
	v_add_f32_e32 v72, v82, v72
	v_exp_f32_e32 v86, v81
	v_add_f32_e32 v72, v80, v72
	v_add_f32_e32 v72, v83, v72
	v_cvt_pk_bf16_f32 v74, v76, v77
	v_cvt_pk_bf16_f32 v75, v78, v79
	v_cvt_pk_bf16_f32 v76, v82, v80
	v_cvt_pk_bf16_f32 v77, v83, v84
	ds_read_b64_tr_b16 v[80:81], v119 offset:8448
	ds_read_b64_tr_b16 v[78:79], v119
	ds_read_b64_tr_b16 v[82:83], v119 offset:32
	v_pk_mul_f32 v[70:71], v[70:71], v[86:87] op_sel_hi:[1,0]
	v_pk_mul_f32 v[68:69], v[68:69], v[86:87] op_sel_hi:[1,0]
	v_add_f32_e32 v72, v84, v72
	ds_read_b64_tr_b16 v[84:85], v119 offset:8480
	s_waitcnt lgkmcnt(2)
	v_mfma_f32_16x16x32_bf16 v[68:71], v[78:81], v[74:77], v[68:71]
	ds_read_b64_tr_b16 v[78:79], v119 offset:64
	ds_read_b64_tr_b16 v[80:81], v119 offset:8512
	v_pk_mul_f32 v[66:67], v[66:67], v[86:87] op_sel_hi:[1,0]
	v_pk_mul_f32 v[64:65], v[64:65], v[86:87] op_sel_hi:[1,0]
	v_pk_mul_f32 v[62:63], v[62:63], v[86:87] op_sel_hi:[1,0]
	v_pk_mul_f32 v[60:61], v[60:61], v[86:87] op_sel_hi:[1,0]
	s_waitcnt lgkmcnt(0)
	v_mfma_f32_16x16x32_bf16 v[64:67], v[78:81], v[74:77], v[64:67]
	ds_read_b64_tr_b16 v[78:79], v119 offset:96
	ds_read_b64_tr_b16 v[80:81], v119 offset:8544
	v_pk_mul_f32 v[26:27], v[26:27], v[86:87] op_sel_hi:[1,0]
	v_pk_mul_f32 v[24:25], v[24:25], v[86:87] op_sel_hi:[1,0]
	s_waitcnt lgkmcnt(0)
	v_mfma_f32_16x16x32_bf16 v[60:63], v[78:81], v[74:77], v[60:63]
	v_mul_f32_e64 v58, v58, v86
	v_mul_f32_e64 v59, v59, v86
	v_pk_mul_f32 v[56:57], v[56:57], v[86:87] op_sel_hi:[1,0]
	v_pk_mul_f32 v[50:51], v[50:51], v[86:87] op_sel_hi:[1,0]
	v_mfma_f32_16x16x32_bf16 v[24:27], v[82:85], v[74:77], v[24:27]
	ds_read_b64_tr_b16 v[80:81], v119 offset:8576
	ds_read_b64_tr_b16 v[78:79], v119 offset:128
	ds_read_b64_tr_b16 v[82:83], v119 offset:160
	ds_read_b64_tr_b16 v[84:85], v119 offset:8608
	v_pk_mul_f32 v[48:49], v[48:49], v[86:87] op_sel_hi:[1,0]
	s_waitcnt lgkmcnt(2)
	v_mfma_f32_16x16x32_bf16 v[56:59], v[78:81], v[74:77], v[56:59]
	ds_read_b64_tr_b16 v[78:79], v119 offset:192
	ds_read_b64_tr_b16 v[80:81], v119 offset:8640
	v_pk_mul_f32 v[54:55], v[54:55], v[86:87] op_sel_hi:[1,0]
	v_pk_mul_f32 v[52:53], v[52:53], v[86:87] op_sel_hi:[1,0]
	s_waitcnt lgkmcnt(0)
	v_mfma_f32_16x16x32_bf16 v[48:51], v[78:81], v[74:77], v[48:51]
	ds_read_b64_tr_b16 v[78:79], v119 offset:224
	ds_read_b64_tr_b16 v[80:81], v119 offset:8672
	v_pk_mul_f32 v[46:47], v[46:47], v[86:87] op_sel_hi:[1,0]
	v_pk_mul_f32 v[44:45], v[44:45], v[86:87] op_sel_hi:[1,0]
	v_mfma_f32_16x16x32_bf16 v[52:55], v[82:85], v[74:77], v[52:55]
	v_mul_f32_e64 v42, v42, v86
	v_mul_f32_e64 v43, v43, v86
	v_pk_mul_f32 v[40:41], v[40:41], v[86:87] op_sel_hi:[1,0]
	v_pk_mul_f32 v[22:23], v[22:23], v[86:87] op_sel_hi:[1,0]
	s_waitcnt lgkmcnt(0)
	v_mfma_f32_16x16x32_bf16 v[44:47], v[78:81], v[74:77], v[44:47]
	ds_read_b64_tr_b16 v[80:81], v119 offset:8704
	ds_read_b64_tr_b16 v[78:79], v119 offset:256
	ds_read_b64_tr_b16 v[82:83], v119 offset:288
	ds_read_b64_tr_b16 v[84:85], v119 offset:8736
	v_pk_mul_f32 v[20:21], v[20:21], v[86:87] op_sel_hi:[1,0]
	s_waitcnt lgkmcnt(2)
	v_mfma_f32_16x16x32_bf16 v[40:43], v[78:81], v[74:77], v[40:43]
	ds_read_b64_tr_b16 v[78:79], v119 offset:320
	ds_read_b64_tr_b16 v[80:81], v119 offset:8768
	v_pk_mul_f32 v[30:31], v[30:31], v[86:87] op_sel_hi:[1,0]
	v_pk_mul_f32 v[28:29], v[28:29], v[86:87] op_sel_hi:[1,0]
	s_waitcnt lgkmcnt(0)
	v_mfma_f32_16x16x32_bf16 v[20:23], v[78:81], v[74:77], v[20:23]
	ds_read_b64_tr_b16 v[78:79], v119 offset:352
	ds_read_b64_tr_b16 v[80:81], v119 offset:8800
	v_pk_mul_f32 v[18:19], v[18:19], v[86:87] op_sel_hi:[1,0]
	v_pk_mul_f32 v[16:17], v[16:17], v[86:87] op_sel_hi:[1,0]
	v_mfma_f32_16x16x32_bf16 v[28:31], v[82:85], v[74:77], v[28:31]
	v_mul_f32_e64 v14, v14, v86
	v_mul_f32_e64 v15, v15, v86
	v_pk_mul_f32 v[12:13], v[12:13], v[86:87] op_sel_hi:[1,0]
	v_pk_mul_f32 v[6:7], v[6:7], v[86:87] op_sel_hi:[1,0]
	s_waitcnt lgkmcnt(0)
	v_mfma_f32_16x16x32_bf16 v[16:19], v[78:81], v[74:77], v[16:19]
	ds_read_b64_tr_b16 v[80:81], v119 offset:8832
	ds_read_b64_tr_b16 v[78:79], v119 offset:384
	ds_read_b64_tr_b16 v[82:83], v119 offset:416
	ds_read_b64_tr_b16 v[84:85], v119 offset:8864
	v_pk_mul_f32 v[4:5], v[4:5], v[86:87] op_sel_hi:[1,0]
	s_waitcnt lgkmcnt(2)
	v_mfma_f32_16x16x32_bf16 v[12:15], v[78:81], v[74:77], v[12:15]
	ds_read_b64_tr_b16 v[78:79], v119 offset:448
	ds_read_b64_tr_b16 v[80:81], v119 offset:8896
	v_pk_mul_f32 v[10:11], v[10:11], v[86:87] op_sel_hi:[1,0]
	v_pk_mul_f32 v[8:9], v[8:9], v[86:87] op_sel_hi:[1,0]
	s_waitcnt lgkmcnt(0)
	v_mfma_f32_16x16x32_bf16 v[4:7], v[78:81], v[74:77], v[4:7]
	ds_read_b64_tr_b16 v[78:79], v119 offset:480
	ds_read_b64_tr_b16 v[80:81], v119 offset:8928
	v_pk_mul_f32 v[2:3], v[2:3], v[86:87] op_sel_hi:[1,0]
	v_pk_mul_f32 v[0:1], v[0:1], v[86:87] op_sel_hi:[1,0]
	v_mfma_f32_16x16x32_bf16 v[8:11], v[82:85], v[74:77], v[8:11]
	s_waitcnt lgkmcnt(0)
	v_fmac_f32_e32 v72, v129, v86
	s_waitcnt lgkmcnt(0)
	v_mfma_f32_16x16x32_bf16 v[0:3], v[78:81], v[74:77], v[0:3]
	v_mov_b32_e32 v128, v73
	s_cbranch_scc0 .LBB0_136
	ds_bpermute_b32 v73, v113, v72
	v_mov_b32_e32 v124, v123
	v_mov_b32_e32 v125, v122
	v_mov_b32_e32 v126, v121
	v_mov_b32_e32 v127, v120
	s_waitcnt lgkmcnt(0)
	v_add_f32_e32 v72, v72, v73
	ds_bpermute_b32 v73, v114, v72
	s_mov_b32 s2, s25
	s_waitcnt lgkmcnt(0)
	v_add_f32_e32 v72, v72, v73
	v_div_scale_f32 v73, s[0:1], v72, v72, 1.0
	v_rcp_f32_e32 v74, v73
	s_lshl_b64 s[0:1], s[76:77], 13
	s_mov_b32 s76, s38
	v_fma_f32 v75, -v73, v74, 1.0
	v_fmac_f32_e32 v74, v75, v74
	v_div_scale_f32 v75, vcc, 1.0, v72, 1.0
	v_mul_f32_e32 v76, v75, v74
	v_fma_f32 v77, -v73, v76, v75
	v_fmac_f32_e32 v76, v77, v74
	v_fma_f32 v73, -v73, v76, v75
	v_div_fmas_f32 v73, v73, v74, v76
	v_div_fixup_f32 v72, v73, v72, 1.0
	v_pk_mul_f32 v[24:25], v[24:25], v[72:73] op_sel_hi:[1,0]
	v_pk_mul_f32 v[26:27], v[26:27], v[72:73] op_sel_hi:[1,0]
	v_lshl_add_u64 v[74:75], v[104:105], 0, s[0:1]
	v_cvt_pk_bf16_f32 v24, v24, v25
	v_cvt_pk_bf16_f32 v25, v26, v27
	global_store_dwordx2 v[74:75], v[24:25], off offset:32
	v_pk_mul_f32 v[24:25], v[64:65], v[72:73] op_sel_hi:[1,0]
	v_pk_mul_f32 v[26:27], v[66:67], v[72:73] op_sel_hi:[1,0]
	v_cvt_pk_bf16_f32 v24, v24, v25
	v_cvt_pk_bf16_f32 v25, v26, v27
	global_store_dwordx2 v[74:75], v[24:25], off offset:64
	v_pk_mul_f32 v[24:25], v[60:61], v[72:73] op_sel_hi:[1,0]
	v_pk_mul_f32 v[26:27], v[62:63], v[72:73] op_sel_hi:[1,0]
	v_cvt_pk_bf16_f32 v24, v24, v25
	v_cvt_pk_bf16_f32 v25, v26, v27
	global_store_dwordx2 v[74:75], v[24:25], off offset:96
	v_pk_mul_f32 v[24:25], v[56:57], v[72:73] op_sel_hi:[1,0]
	v_pk_mul_f32 v[26:27], v[58:59], v[72:73] op_sel_hi:[1,0]
	v_cvt_pk_bf16_f32 v24, v24, v25
	v_cvt_pk_bf16_f32 v25, v26, v27
	global_store_dwordx2 v[74:75], v[24:25], off offset:128
	v_pk_mul_f32 v[24:25], v[52:53], v[72:73] op_sel_hi:[1,0]
	v_pk_mul_f32 v[26:27], v[54:55], v[72:73] op_sel_hi:[1,0]
	v_cvt_pk_bf16_f32 v24, v24, v25
	v_cvt_pk_bf16_f32 v25, v26, v27
	global_store_dwordx2 v[74:75], v[24:25], off offset:160
	v_pk_mul_f32 v[24:25], v[48:49], v[72:73] op_sel_hi:[1,0]
	v_pk_mul_f32 v[26:27], v[50:51], v[72:73] op_sel_hi:[1,0]
	v_cvt_pk_bf16_f32 v24, v24, v25
	v_cvt_pk_bf16_f32 v25, v26, v27
	global_store_dwordx2 v[74:75], v[24:25], off offset:192
	v_pk_mul_f32 v[24:25], v[44:45], v[72:73] op_sel_hi:[1,0]
	v_pk_mul_f32 v[26:27], v[46:47], v[72:73] op_sel_hi:[1,0]
	v_cvt_pk_bf16_f32 v24, v24, v25
	v_cvt_pk_bf16_f32 v25, v26, v27
	global_store_dwordx2 v[74:75], v[24:25], off offset:224
	v_pk_mul_f32 v[24:25], v[40:41], v[72:73] op_sel_hi:[1,0]
	v_pk_mul_f32 v[26:27], v[42:43], v[72:73] op_sel_hi:[1,0]
	v_cvt_pk_bf16_f32 v24, v24, v25
	v_cvt_pk_bf16_f32 v25, v26, v27
	v_pk_mul_f32 v[68:69], v[68:69], v[72:73] op_sel_hi:[1,0]
	v_pk_mul_f32 v[70:71], v[70:71], v[72:73] op_sel_hi:[1,0]
	global_store_dwordx2 v[74:75], v[24:25], off offset:256
	v_pk_mul_f32 v[24:25], v[28:29], v[72:73] op_sel_hi:[1,0]
	v_pk_mul_f32 v[26:27], v[30:31], v[72:73] op_sel_hi:[1,0]
	v_pk_mul_f32 v[20:21], v[20:21], v[72:73] op_sel_hi:[1,0]
	v_pk_mul_f32 v[22:23], v[22:23], v[72:73] op_sel_hi:[1,0]
	v_pk_mul_f32 v[16:17], v[16:17], v[72:73] op_sel_hi:[1,0]
	v_pk_mul_f32 v[18:19], v[18:19], v[72:73] op_sel_hi:[1,0]
	v_pk_mul_f32 v[12:13], v[12:13], v[72:73] op_sel_hi:[1,0]
	v_pk_mul_f32 v[14:15], v[14:15], v[72:73] op_sel_hi:[1,0]
	v_pk_mul_f32 v[8:9], v[8:9], v[72:73] op_sel_hi:[1,0]
	v_pk_mul_f32 v[10:11], v[10:11], v[72:73] op_sel_hi:[1,0]
	v_pk_mul_f32 v[4:5], v[4:5], v[72:73] op_sel_hi:[1,0]
	v_pk_mul_f32 v[6:7], v[6:7], v[72:73] op_sel_hi:[1,0]
	v_pk_mul_f32 v[0:1], v[0:1], v[72:73] op_sel_hi:[1,0]
	v_pk_mul_f32 v[2:3], v[2:3], v[72:73] op_sel_hi:[1,0]
	v_cvt_pk_bf16_f32 v68, v68, v69
	v_cvt_pk_bf16_f32 v69, v70, v71
	v_cvt_pk_bf16_f32 v24, v24, v25
	v_cvt_pk_bf16_f32 v25, v26, v27
	v_cvt_pk_bf16_f32 v20, v20, v21
	v_cvt_pk_bf16_f32 v21, v22, v23
	v_cvt_pk_bf16_f32 v16, v16, v17
	v_cvt_pk_bf16_f32 v17, v18, v19
	v_cvt_pk_bf16_f32 v12, v12, v13
	v_cvt_pk_bf16_f32 v13, v14, v15
	v_cvt_pk_bf16_f32 v8, v8, v9
	v_cvt_pk_bf16_f32 v9, v10, v11
	v_cvt_pk_bf16_f32 v4, v4, v5
	v_cvt_pk_bf16_f32 v5, v6, v7
	v_cvt_pk_bf16_f32 v0, v0, v1
	v_cvt_pk_bf16_f32 v1, v2, v3
	s_and_b64 vcc, exec, s[40:41]
	global_store_dwordx2 v[74:75], v[68:69], off
	global_store_dwordx2 v[74:75], v[24:25], off offset:288
	global_store_dwordx2 v[74:75], v[20:21], off offset:320
	global_store_dwordx2 v[74:75], v[16:17], off offset:352
	global_store_dwordx2 v[74:75], v[12:13], off offset:384
	global_store_dwordx2 v[74:75], v[8:9], off offset:416
	global_store_dwordx2 v[74:75], v[4:5], off offset:448
	global_store_dwordx2 v[74:75], v[0:1], off offset:480
	s_cbranch_vccz .LBB0_128

.LBB0_149:
	s_lshl_b32 s1, s2, 3
	s_lshl_b32 s0, s3, 12
	v_readlane_b32 s4, v253, 11
	s_add_i32 s27, s0, s1
	v_readlane_b32 s5, v253, 12
	v_add_u32_e32 v2, s27, v33
	s_movk_i32 s1, 0x3400
	v_mov_b64_e32 v[0:1], s[4:5]
	v_mad_i64_i32 v[0:1], s[24:25], v2, s1, v[0:1]
	v_mov_b32_e32 v109, v32
	v_lshl_add_u64 v[0:1], v[0:1], 0, v[108:109]
	v_mov_b32_e32 v111, v32
	v_lshl_add_u64 v[0:1], v[0:1], 0, v[110:111]
	s_mov_b64 s[24:25], 0x1d302200
	v_lshl_add_u64 v[2:3], v[0:1], 0, s[24:25]
	v_add_co_u32_e32 v0, vcc, 0x1d302000, v0
	s_ashr_i32 s1, s0, 31
	s_nop 0
	v_addc_co_u32_e32 v1, vcc, 0, v1, vcc
	global_load_dwordx4 v[40:43], v[2:3], off offset:32
	global_load_dwordx4 v[44:47], v[2:3], off offset:64
	global_load_dwordx4 v[48:51], v[2:3], off offset:96
	global_load_dwordx4 v[52:55], v[2:3], off offset:128
	global_load_dwordx4 v[56:59], v[2:3], off offset:160
	global_load_dwordx4 v[60:63], v[2:3], off offset:192
	global_load_dwordx4 v[64:67], v[0:1], off offset:512
	global_load_dwordx4 v[68:71], v[2:3], off offset:224
	v_add_u32_e32 v0, s27, v35
	v_ashrrev_i32_e32 v1, 31, v0
	v_readlane_b32 s4, v253, 40
	s_ashr_i32 s38, s2, 3
	s_lshl_b64 s[2:3], s[0:1], 8
	v_readlane_b32 s0, v253, 38
	v_lshlrev_b64 v[0:1], 6, v[0:1]
	v_readlane_b32 s5, v253, 41
	s_add_u32 s0, s0, s2
	v_readlane_b32 s1, v253, 39
	v_lshl_add_u64 v[0:1], s[4:5], 0, v[0:1]
	s_addc_u32 s1, s1, s3
	global_load_dwordx4 v[72:75], v[0:1], off offset:48
	global_load_dwordx4 v[76:79], v[0:1], off offset:32
	global_load_dwordx4 v[80:83], v[0:1], off offset:16
	global_load_dwordx4 v[84:87], v[0:1], off
	v_lshl_add_u64 v[0:1], s[0:1], 0, v[104:105]
	v_add_co_u32_e32 v2, vcc, 0x2000, v0
	s_nop 1
	v_addc_co_u32_e32 v3, vcc, 0, v1, vcc
	global_load_dwordx4 v[92:95], v[2:3], off
	global_load_dwordx4 v[88:91], v[0:1], off
	s_cmp_lt_i32 s38, 1
	s_cbranch_scc1 .LBB0_151
	v_add_co_u32_e32 v2, vcc, 0x4000, v0
	s_nop 1
	v_addc_co_u32_e32 v3, vcc, 0, v1, vcc
	v_add_co_u32_e32 v0, vcc, 0x6000, v0
	s_nop 1
	v_addc_co_u32_e32 v1, vcc, 0, v1, vcc
	global_load_dwordx4 v[96:99], v[2:3], off
	global_load_dwordx4 v[100:103], v[0:1], off
.LBB0_151:
	s_cmp_lt_i32 s38, 0
	s_cselect_b64 s[80:81], -1, 0
	s_cmp_gt_i32 s38, -1
	s_cselect_b64 s[0:1], -1, 0
	s_and_b64 vcc, exec, s[80:81]
	s_cbranch_vccnz .LBB0_160
	v_lshl_add_u64 v[112:113], v[106:107], 0, s[2:3]
	s_mov_b32 s2, 3
	v_mov_b32_e32 v109, v203
	v_mov_b32_e32 v207, 0x25000
	s_waitcnt lgkmcnt(0)
.Lidx_even:
	s_barrier
	s_add_i32 s3, s2, -1
	s_add_i32 s24, s2, -3
	s_cmp_ge_i32 s24, s38
	s_cbranch_scc1 .Lidx_e_last
	s_waitcnt vmcnt(2)
	s_branch .Lidx_e_st

.Lidx_e_st:
	ds_write_b128 v205, v[88:91]
	ds_write_b128 v205, v[92:95] offset:8704
	s_waitcnt lgkmcnt(0)
	s_barrier
	s_cmp_gt_i32 s3, s38
	s_cbranch_scc1 .Lidx_e_nopf
	v_add_co_u32_e32 v248, vcc, 0xffffa000, v112
	s_nop 1
	v_addc_co_u32_e32 v249, vcc, -1, v113, vcc
	global_load_dwordx4 v[88:91], v[248:249], off
	v_add_co_u32_e32 v248, vcc, 0xffffc000, v112
	s_nop 1
	v_addc_co_u32_e32 v249, vcc, -1, v113, vcc
	global_load_dwordx4 v[92:95], v[248:249], off
.Lidx_e_nopf:
	ds_read_b128 v[136:139], v206
	ds_read_b128 v[140:143], v206 offset:32
	ds_read_b128 v[208:211], v206 offset:64
	ds_read_b128 v[212:215], v206 offset:96
	s_waitcnt lgkmcnt(3)
	v_mfma_f32_32x32x16_bf16 v[0:15], v[64:67], v[136:139], 0
	ds_read_b128 v[136:139], v206 offset:128
	v_add_f32_e32 v216, v216, v232
	v_add_f32_e32 v217, v217, v233
	v_max_f32_e32 v216, 0, v216
	v_max_f32_e32 v217, 0, v217
	v_fma_f32 v216, v84, v216, 0
	v_add_f32_e32 v218, v218, v234
	s_waitcnt lgkmcnt(3)
	v_mfma_f32_32x32x16_bf16 v[16:31], v[40:43], v[140:143], 0
	ds_read_b128 v[140:143], v206 offset:160
	v_fmac_f32_e32 v216, v85, v217
	v_max_f32_e32 v218, 0, v218
	v_add_f32_e32 v219, v219, v235
	v_fmac_f32_e32 v216, v86, v218
	v_max_f32_e32 v219, 0, v219
	v_add_f32_e32 v220, v220, v236
	s_waitcnt lgkmcnt(3)
	v_mfma_f32_32x32x16_bf16 v[0:15], v[44:47], v[208:211], v[0:15]
	ds_read_b128 v[208:211], v206 offset:192
	v_fmac_f32_e32 v216, v87, v219
	v_max_f32_e32 v220, 0, v220
	v_add_f32_e32 v221, v221, v237
	v_fmac_f32_e32 v216, v80, v220
	v_max_f32_e32 v221, 0, v221
	v_add_f32_e32 v222, v222, v238
	s_waitcnt lgkmcnt(3)
	v_mfma_f32_32x32x16_bf16 v[16:31], v[48:51], v[212:215], v[16:31]
	ds_read_b128 v[212:215], v206 offset:224
	v_fmac_f32_e32 v216, v81, v221
	v_max_f32_e32 v222, 0, v222
	v_add_f32_e32 v223, v223, v239
	v_fmac_f32_e32 v216, v82, v222
	v_max_f32_e32 v223, 0, v223
	v_add_f32_e32 v224, v224, v240
	s_waitcnt lgkmcnt(3)
	v_mfma_f32_32x32x16_bf16 v[0:15], v[52:55], v[136:139], v[0:15]
	v_fmac_f32_e32 v216, v83, v223
	v_max_f32_e32 v224, 0, v224
	v_add_f32_e32 v225, v225, v241
	v_fmac_f32_e32 v216, v76, v224
	v_max_f32_e32 v225, 0, v225
	v_add_f32_e32 v226, v226, v242
	s_waitcnt lgkmcnt(2)
	v_mfma_f32_32x32x16_bf16 v[16:31], v[56:59], v[140:143], v[16:31]
	v_fmac_f32_e32 v216, v77, v225
	v_max_f32_e32 v226, 0, v226
	v_add_f32_e32 v227, v227, v243
	v_fmac_f32_e32 v216, v78, v226
	v_max_f32_e32 v227, 0, v227
	v_add_f32_e32 v228, v228, v244
	s_waitcnt lgkmcnt(1)
	v_mfma_f32_32x32x16_bf16 v[0:15], v[60:63], v[208:211], v[0:15]
	v_fmac_f32_e32 v216, v79, v227
	v_max_f32_e32 v228, 0, v228
	v_add_f32_e32 v229, v229, v245
	v_fmac_f32_e32 v216, v72, v228
	v_max_f32_e32 v229, 0, v229
	v_add_f32_e32 v230, v230, v246
	s_waitcnt lgkmcnt(0)
	v_mfma_f32_32x32x16_bf16 v[16:31], v[68:71], v[212:215], v[16:31]
	v_fmac_f32_e32 v216, v73, v229
	v_max_f32_e32 v230, 0, v230
	v_add_f32_e32 v231, v231, v247
	v_fmac_f32_e32 v216, v74, v230
	v_max_f32_e32 v231, 0, v231
	v_fmac_f32_e32 v216, v75, v231
	ds_write_b32 v207, v216
	s_nop 0
	v_mov_b32_e32 v207, v109
	s_add_i32 s24, s2, -3
	s_cmp_ge_i32 s24, s38
	s_cbranch_scc1 .Lidx_inc
	s_barrier
	s_add_i32 s24, s2, -2
	s_cmp_ge_i32 s24, s38
	s_cbranch_scc1 .Lidx_o_last
	s_waitcnt vmcnt(2)
	s_branch .Lidx_o_st

.Lidx_o_st:
	ds_write_b128 v205, v[96:99]
	ds_write_b128 v205, v[100:103] offset:8704
	s_waitcnt lgkmcnt(0)
	s_barrier
	s_cmp_gt_i32 s2, s38
	s_cbranch_scc1 .Lidx_o_nopf
	v_add_co_u32_e32 v248, vcc, 0xffffe000, v112
	s_nop 1
	v_addc_co_u32_e32 v249, vcc, -1, v113, vcc
	global_load_dwordx4 v[96:99], v[248:249], off
	global_load_dwordx4 v[100:103], v[112:113], off
.Lidx_o_nopf:
	ds_read_b128 v[136:139], v206
	ds_read_b128 v[140:143], v206 offset:32
	ds_read_b128 v[208:211], v206 offset:64
	ds_read_b128 v[212:215], v206 offset:96
	s_waitcnt lgkmcnt(3)
	v_mfma_f32_32x32x16_bf16 v[216:231], v[64:67], v[136:139], 0
	ds_read_b128 v[136:139], v206 offset:128
	v_add_f32_e32 v0, v0, v16
	v_add_f32_e32 v1, v1, v17
	v_max_f32_e32 v0, 0, v0
	v_max_f32_e32 v1, 0, v1
	v_fma_f32 v0, v84, v0, 0
	v_add_f32_e32 v2, v2, v18
	s_waitcnt lgkmcnt(3)
	v_mfma_f32_32x32x16_bf16 v[232:247], v[40:43], v[140:143], 0
	ds_read_b128 v[140:143], v206 offset:160
	v_fmac_f32_e32 v0, v85, v1
	v_max_f32_e32 v2, 0, v2
	v_add_f32_e32 v3, v3, v19
	v_fmac_f32_e32 v0, v86, v2
	v_max_f32_e32 v3, 0, v3
	v_add_f32_e32 v4, v4, v20
	s_waitcnt lgkmcnt(3)
	v_mfma_f32_32x32x16_bf16 v[216:231], v[44:47], v[208:211], v[216:231]
	ds_read_b128 v[208:211], v206 offset:192
	v_fmac_f32_e32 v0, v87, v3
	v_max_f32_e32 v4, 0, v4
	v_add_f32_e32 v5, v5, v21
	v_fmac_f32_e32 v0, v80, v4
	v_max_f32_e32 v5, 0, v5
	v_add_f32_e32 v6, v6, v22
	s_waitcnt lgkmcnt(3)
	v_mfma_f32_32x32x16_bf16 v[232:247], v[48:51], v[212:215], v[232:247]
	ds_read_b128 v[212:215], v206 offset:224
	v_fmac_f32_e32 v0, v81, v5
	v_max_f32_e32 v6, 0, v6
	v_add_f32_e32 v7, v7, v23
	v_fmac_f32_e32 v0, v82, v6
	v_max_f32_e32 v7, 0, v7
	v_add_f32_e32 v8, v8, v24
	s_waitcnt lgkmcnt(3)
	v_mfma_f32_32x32x16_bf16 v[216:231], v[52:55], v[136:139], v[216:231]
	v_fmac_f32_e32 v0, v83, v7
	v_max_f32_e32 v8, 0, v8
	v_add_f32_e32 v9, v9, v25
	v_fmac_f32_e32 v0, v76, v8
	v_max_f32_e32 v9, 0, v9
	v_add_f32_e32 v10, v10, v26
	s_waitcnt lgkmcnt(2)
	v_mfma_f32_32x32x16_bf16 v[232:247], v[56:59], v[140:143], v[232:247]
	v_fmac_f32_e32 v0, v77, v9
	v_max_f32_e32 v10, 0, v10
	v_add_f32_e32 v11, v11, v27
	v_fmac_f32_e32 v0, v78, v10
	v_max_f32_e32 v11, 0, v11
	v_add_f32_e32 v12, v12, v28
	s_waitcnt lgkmcnt(1)
	v_mfma_f32_32x32x16_bf16 v[216:231], v[60:63], v[208:211], v[216:231]
	v_fmac_f32_e32 v0, v79, v11
	v_max_f32_e32 v12, 0, v12
	v_add_f32_e32 v13, v13, v29
	v_fmac_f32_e32 v0, v72, v12
	v_max_f32_e32 v13, 0, v13
	v_add_f32_e32 v14, v14, v30
	s_waitcnt lgkmcnt(0)
	v_mfma_f32_32x32x16_bf16 v[232:247], v[68:71], v[212:215], v[232:247]
	v_fmac_f32_e32 v0, v73, v13
	v_max_f32_e32 v14, 0, v14
	v_add_f32_e32 v15, v15, v31
	v_fmac_f32_e32 v0, v74, v14
	v_max_f32_e32 v15, 0, v15
	v_fmac_f32_e32 v0, v75, v15
	ds_write_b32 v207, v0
	s_nop 0
	v_add_u32_e32 v207, 0x100, v109
.Lidx_inc:
	s_mov_b64 s[24:25], 0x8000
	s_add_i32 s2, s2, 2
	v_lshl_add_u64 v[112:113], v[112:113], 0, s[24:25]
	s_cmp_gt_i32 s3, s38
	v_add_u32_e32 v109, 0x200, v109
	s_cbranch_scc0 .Lidx_even
	s_bitcmp1_b32 s38, 0
	s_cbranch_scc1 .Lidx_fin_odd
	s_nop 11
	v_add_f32_e32 v0, v0, v16
	v_add_f32_e32 v1, v1, v17
	v_max_f32_e32 v0, 0, v0
	v_max_f32_e32 v1, 0, v1
	v_fma_f32 v0, v84, v0, 0
	v_add_f32_e32 v2, v2, v18
	v_fmac_f32_e32 v0, v85, v1
	v_max_f32_e32 v2, 0, v2
	v_add_f32_e32 v3, v3, v19
	v_fmac_f32_e32 v0, v86, v2
	v_max_f32_e32 v3, 0, v3
	v_add_f32_e32 v4, v4, v20
	v_fmac_f32_e32 v0, v87, v3
	v_max_f32_e32 v4, 0, v4
	v_add_f32_e32 v5, v5, v21
	v_fmac_f32_e32 v0, v80, v4
	v_max_f32_e32 v5, 0, v5
	v_add_f32_e32 v6, v6, v22
	v_fmac_f32_e32 v0, v81, v5
	v_max_f32_e32 v6, 0, v6
	v_add_f32_e32 v7, v7, v23
	v_fmac_f32_e32 v0, v82, v6
	v_max_f32_e32 v7, 0, v7
	v_add_f32_e32 v8, v8, v24
	v_fmac_f32_e32 v0, v83, v7
	v_max_f32_e32 v8, 0, v8
	v_add_f32_e32 v9, v9, v25
	v_fmac_f32_e32 v0, v76, v8
	v_max_f32_e32 v9, 0, v9
	v_add_f32_e32 v10, v10, v26
	v_fmac_f32_e32 v0, v77, v9
	v_max_f32_e32 v10, 0, v10
	v_add_f32_e32 v11, v11, v27
	v_fmac_f32_e32 v0, v78, v10
	v_max_f32_e32 v11, 0, v11
	v_add_f32_e32 v12, v12, v28
	v_fmac_f32_e32 v0, v79, v11
	v_max_f32_e32 v12, 0, v12
	v_add_f32_e32 v13, v13, v29
	v_fmac_f32_e32 v0, v72, v12
	v_max_f32_e32 v13, 0, v13
	v_add_f32_e32 v14, v14, v30
	v_fmac_f32_e32 v0, v73, v13
	v_max_f32_e32 v14, 0, v14
	v_add_f32_e32 v15, v15, v31
	v_fmac_f32_e32 v0, v74, v14
	v_max_f32_e32 v15, 0, v15
	v_fmac_f32_e32 v0, v75, v15
	ds_write_b32 v207, v0
	s_branch .LBB0_160
.Lidx_fin_odd:
	s_nop 11
	v_add_f32_e32 v216, v216, v232
	v_add_f32_e32 v217, v217, v233
	v_max_f32_e32 v216, 0, v216
	v_max_f32_e32 v217, 0, v217
	v_fma_f32 v216, v84, v216, 0
	v_add_f32_e32 v218, v218, v234
	v_fmac_f32_e32 v216, v85, v217
	v_max_f32_e32 v218, 0, v218
	v_add_f32_e32 v219, v219, v235
	v_fmac_f32_e32 v216, v86, v218
	v_max_f32_e32 v219, 0, v219
	v_add_f32_e32 v220, v220, v236
	v_fmac_f32_e32 v216, v87, v219
	v_max_f32_e32 v220, 0, v220
	v_add_f32_e32 v221, v221, v237
	v_fmac_f32_e32 v216, v80, v220
	v_max_f32_e32 v221, 0, v221
	v_add_f32_e32 v222, v222, v238
	v_fmac_f32_e32 v216, v81, v221
	v_max_f32_e32 v222, 0, v222
	v_add_f32_e32 v223, v223, v239
	v_fmac_f32_e32 v216, v82, v222
	v_max_f32_e32 v223, 0, v223
	v_add_f32_e32 v224, v224, v240
	v_fmac_f32_e32 v216, v83, v223
	v_max_f32_e32 v224, 0, v224
	v_add_f32_e32 v225, v225, v241
	v_fmac_f32_e32 v216, v76, v224
	v_max_f32_e32 v225, 0, v225
	v_add_f32_e32 v226, v226, v242
	v_fmac_f32_e32 v216, v77, v225
	v_max_f32_e32 v226, 0, v226
	v_add_f32_e32 v227, v227, v243
	v_fmac_f32_e32 v216, v78, v226
	v_max_f32_e32 v227, 0, v227
	v_add_f32_e32 v228, v228, v244
	v_fmac_f32_e32 v216, v79, v227
	v_max_f32_e32 v228, 0, v228
	v_add_f32_e32 v229, v229, v245
	v_fmac_f32_e32 v216, v72, v228
	v_max_f32_e32 v229, 0, v229
	v_add_f32_e32 v230, v230, v246
	v_fmac_f32_e32 v216, v73, v229
	v_max_f32_e32 v230, 0, v230
	v_add_f32_e32 v231, v231, v247
	v_fmac_f32_e32 v216, v74, v230
	v_max_f32_e32 v231, 0, v231
	v_fmac_f32_e32 v216, v75, v231
	ds_write_b32 v207, v216
